# fnet_combine seam loads speculated at loop head (single round trip per iteration); accumulator zeroing via v_mov_b64
# speedup vs baseline: 1.0089x; 1.0059x over previous
; template <class Epi>
; __device__ __forceinline__ void gemm_phase(LAS unsigned char* lds, const int K, const unsigned lda_b, const unsigned ldb_b, const Map& M, const Epi& E) {
;     ...
;     const bool has_next = (ui + 1 < nunits);
;     load_unit(lds, has_next ? ui + 1 : ui, nxt);
;     if (Epi::PERM) nxt.b1 = nxt.b0 + (size_t)32 * ldb_b;
;     ...
; #pragma unroll
;     for (int a = 0; a < 2; ++a)
; #pragma unroll
;       for (int b = 0; b < 2; ++b)
; #pragma unroll
;         for (int m = 0; m < 4; ++m)
; #pragma unroll
;           for (int n = 0; n < 2; ++n) acc[a][b][m][n] = (f32x4){0.f, 0.f, 0.f, 0.f};
;     cur = nxt; ++ui;
.LBB0_234:
	s_mov_b32 s0, s76
	s_add_i32 s76, s76, 1
	s_cmp_lt_i32 s76, s1
	s_cselect_b32 s0, s76, s0
	s_mul_i32 s0, s0, 48
	s_add_i32 s0, s0, 0
	s_add_i32 s0, s0, 0x20000
	v_mov_b32_e32 v4, s0
	ds_read_b128 v[0:3], v4
	ds_read2_b64 v[128:131], v4 offset0:3 offset1:4
	s_mov_b32 s31, -2
	s_waitcnt lgkmcnt(0)
	v_readfirstlane_b32 s8, v2
	v_readfirstlane_b32 s9, v3
	s_add_u32 s0, s8, 0x20000
	s_addc_u32 s28, s9, 0
	s_add_u32 s29, s38, 0x20100
	s_addc_u32 s30, s39, 0
	v_readfirstlane_b32 s6, v0
	s_add_u32 s2, s2, 0x80080
	v_mov_b32_e32 v0, 0
	v_readfirstlane_b32 s7, v1
	v_readfirstlane_b32 s40, v128
	v_readfirstlane_b32 s41, v129
	s_addc_u32 s3, s3, 0
	v_mov_b64_e32 v[2:3], 0
	v_mov_b64_e32 v[4:5], 0
	v_mov_b64_e32 v[6:7], 0
	v_mov_b64_e32 v[8:9], 0
	v_mov_b64_e32 v[10:11], 0
	v_mov_b64_e32 v[12:13], 0
	v_mov_b64_e32 v[14:15], 0
	v_mov_b64_e32 v[16:17], 0
	v_mov_b64_e32 v[18:19], 0
	v_mov_b64_e32 v[20:21], 0
	v_mov_b64_e32 v[22:23], 0
	v_mov_b64_e32 v[24:25], 0
	v_mov_b64_e32 v[26:27], 0
	v_mov_b64_e32 v[28:29], 0
	v_mov_b64_e32 v[30:31], 0
	v_mov_b64_e32 v[32:33], 0
	v_mov_b64_e32 v[34:35], 0
	v_mov_b64_e32 v[36:37], 0
	v_mov_b64_e32 v[38:39], 0
	v_mov_b64_e32 v[40:41], 0
	v_mov_b64_e32 v[42:43], 0
	v_mov_b64_e32 v[44:45], 0
	v_mov_b64_e32 v[46:47], 0
	v_mov_b64_e32 v[48:49], 0
	v_mov_b64_e32 v[50:51], 0
	v_mov_b64_e32 v[52:53], 0
	v_mov_b64_e32 v[54:55], 0
	v_mov_b64_e32 v[56:57], 0
	v_mov_b64_e32 v[58:59], 0
	v_mov_b64_e32 v[60:61], 0
	v_mov_b64_e32 v[62:63], 0
	v_mov_b64_e32 v[64:65], 0
	v_mov_b64_e32 v[66:67], 0
	v_mov_b64_e32 v[68:69], 0
	v_mov_b64_e32 v[70:71], 0
	v_mov_b64_e32 v[72:73], 0
	v_mov_b64_e32 v[74:75], 0
	v_mov_b64_e32 v[76:77], 0
	v_mov_b64_e32 v[78:79], 0
	v_mov_b64_e32 v[82:83], 0
	v_mov_b64_e32 v[84:85], 0
	v_mov_b64_e32 v[86:87], 0
	v_mov_b64_e32 v[88:89], 0
	v_mov_b64_e32 v[90:91], 0
	v_mov_b64_e32 v[92:93], 0
	v_mov_b64_e32 v[94:95], 0
	v_mov_b64_e32 v[96:97], 0
	v_mov_b64_e32 v[98:99], 0
	v_mov_b64_e32 v[100:101], 0
	v_mov_b64_e32 v[102:103], 0
	v_mov_b64_e32 v[104:105], 0
	v_mov_b64_e32 v[106:107], 0
	v_mov_b64_e32 v[108:109], 0
	v_mov_b64_e32 v[110:111], 0
	v_mov_b64_e32 v[112:113], 0
	v_mov_b64_e32 v[114:115], 0
	v_mov_b64_e32 v[116:117], 0
	v_mov_b64_e32 v[118:119], 0
	v_mov_b64_e32 v[120:121], 0
	v_mov_b64_e32 v[122:123], 0
	v_mov_b64_e32 v[124:125], 0
	v_mov_b64_e32 v[126:127], 0
	v_mov_b64_e32 v[128:129], 0
	v_mov_b32_e32 v1, 0

; template <class Epi>
; __device__ __forceinline__ void gemm_phase(LAS unsigned char* lds, const int K, const unsigned lda_b, const unsigned ldb_b, const Map& M, const Epi& E) {
;     ...
;     const bool has_next = (ui + 1 < nunits);
;     load_unit(lds, has_next ? ui + 1 : ui, nxt);
;     if (Epi::PERM) nxt.b1 = nxt.b0 + (size_t)32 * ldb_b;
;     ...
; #pragma unroll
;     for (int a = 0; a < 2; ++a)
; #pragma unroll
;       for (int b = 0; b < 2; ++b)
; #pragma unroll
;         for (int m = 0; m < 4; ++m)
; #pragma unroll
;           for (int n = 0; n < 2; ++n) acc[a][b][m][n] = (f32x4){0.f, 0.f, 0.f, 0.f};
;     cur = nxt; ++ui;
.LBB0_256:
	s_mov_b32 s6, s75
	s_add_i32 s75, s75, 1
	s_cmp_lt_i32 s75, s0
	s_cselect_b32 s6, s75, s6
	s_mul_i32 s6, s6, 48
	s_add_i32 s6, s6, 0
	s_add_i32 s6, s6, 0x20000
	v_mov_b32_e32 v0, s6
	ds_read_b128 v[4:7], v0
	ds_read2_b64 v[0:3], v0 offset0:3 offset1:4
	s_mov_b32 s34, -2
	s_waitcnt lgkmcnt(0)
	v_readfirstlane_b32 s40, v6
	v_readfirstlane_b32 s41, v7
	s_add_u32 s28, s40, 0x20000
	s_addc_u32 s29, s41, 0
	s_add_u32 s30, s68, 0x20100
	s_addc_u32 s31, s69, 0
	v_readfirstlane_b32 s8, v4
	s_add_u32 s38, s44, 0x80080
	v_mov_b32_e32 v4, 0
	v_readfirstlane_b32 s9, v5
	v_readfirstlane_b32 s6, v0
	v_readfirstlane_b32 s7, v1
	s_addc_u32 s39, s45, 0
	v_mov_b64_e32 v[6:7], 0
	v_mov_b64_e32 v[8:9], 0
	v_mov_b64_e32 v[10:11], 0
	v_mov_b64_e32 v[12:13], 0
	v_mov_b64_e32 v[14:15], 0
	v_mov_b64_e32 v[16:17], 0
	v_mov_b64_e32 v[18:19], 0
	v_mov_b64_e32 v[20:21], 0
	v_mov_b64_e32 v[22:23], 0
	v_mov_b64_e32 v[24:25], 0
	v_mov_b64_e32 v[26:27], 0
	v_mov_b64_e32 v[28:29], 0
	v_mov_b64_e32 v[30:31], 0
	v_mov_b64_e32 v[32:33], 0
	v_mov_b64_e32 v[34:35], 0
	v_mov_b64_e32 v[36:37], 0
	v_mov_b64_e32 v[38:39], 0
	v_mov_b64_e32 v[40:41], 0
	v_mov_b64_e32 v[42:43], 0
	v_mov_b64_e32 v[44:45], 0
	v_mov_b64_e32 v[46:47], 0
	v_mov_b64_e32 v[48:49], 0
	v_mov_b64_e32 v[50:51], 0
	v_mov_b64_e32 v[52:53], 0
	v_mov_b64_e32 v[54:55], 0
	v_mov_b64_e32 v[56:57], 0
	v_mov_b64_e32 v[58:59], 0
	v_mov_b64_e32 v[60:61], 0
	v_mov_b64_e32 v[62:63], 0
	v_mov_b64_e32 v[64:65], 0
	v_mov_b64_e32 v[66:67], 0
	v_mov_b64_e32 v[68:69], 0
	v_mov_b64_e32 v[70:71], 0
	v_mov_b64_e32 v[72:73], 0
	v_mov_b64_e32 v[74:75], 0
	v_mov_b64_e32 v[76:77], 0
	v_mov_b64_e32 v[78:79], 0
	v_mov_b64_e32 v[82:83], 0
	v_mov_b64_e32 v[84:85], 0
	v_mov_b64_e32 v[86:87], 0
	v_mov_b64_e32 v[88:89], 0
	v_mov_b64_e32 v[90:91], 0
	v_mov_b64_e32 v[92:93], 0
	v_mov_b64_e32 v[94:95], 0
	v_mov_b64_e32 v[96:97], 0
	v_mov_b64_e32 v[98:99], 0
	v_mov_b64_e32 v[100:101], 0
	v_mov_b64_e32 v[102:103], 0
	v_mov_b64_e32 v[104:105], 0
	v_mov_b64_e32 v[106:107], 0
	v_mov_b64_e32 v[108:109], 0
	v_mov_b64_e32 v[110:111], 0
	v_mov_b64_e32 v[112:113], 0
	v_mov_b64_e32 v[114:115], 0
	v_mov_b64_e32 v[116:117], 0
	v_mov_b64_e32 v[118:119], 0
	v_mov_b64_e32 v[120:121], 0
	v_mov_b64_e32 v[122:123], 0
	v_mov_b64_e32 v[124:125], 0
	v_mov_b64_e32 v[126:127], 0
	v_mov_b64_e32 v[128:129], 0
	v_mov_b64_e32 v[130:131], 0
	v_mov_b64_e32 v[132:133], 0
	v_mov_b32_e32 v5, 0

; template <class Epi>
; __device__ __forceinline__ void gemm_phase(LAS unsigned char* lds, const int K, const unsigned lda_b, const unsigned ldb_b, const Map& M, const Epi& E) {
;     ...
;     const bool has_next = (ui + 1 < nunits);
;     load_unit(lds, has_next ? ui + 1 : ui, nxt);
;     if (Epi::PERM) nxt.b1 = nxt.b0 + (size_t)32 * ldb_b;
;     ...
; #pragma unroll
;     for (int a = 0; a < 2; ++a)
; #pragma unroll
;       for (int b = 0; b < 2; ++b)
; #pragma unroll
;         for (int m = 0; m < 4; ++m)
; #pragma unroll
;           for (int n = 0; n < 2; ++n) acc[a][b][m][n] = (f32x4){0.f, 0.f, 0.f, 0.f};
;     cur = nxt; ++ui;
.LBB0_407:
	s_mov_b32 s4, s86
	s_add_i32 s86, s86, 1
	s_cmp_lt_i32 s86, s0
	s_cselect_b32 s4, s86, s4
	s_mul_i32 s4, s4, 48
	s_add_i32 s4, s4, 0
	s_add_i32 s4, s4, 0x20000
	v_mov_b32_e32 v8, s4
	ds_read_b128 v[0:3], v8
	ds_read_b128 v[4:7], v8 offset:16
	ds_read_b64 v[138:139], v8 offset:32
	s_add_u32 s87, s44, 0x100
	s_addc_u32 vcc_lo, s45, 0
	s_waitcnt lgkmcnt(0)
	v_readfirstlane_b32 s4, v0
	s_add_u32 vcc_hi, s42, 0x100
	v_mov_b32_e32 v0, 0
	v_readfirstlane_b32 s5, v1
	v_readfirstlane_b32 s6, v2
	v_readfirstlane_b32 s7, v3
	v_readfirstlane_b32 s8, v4
	v_readfirstlane_b32 s9, v5
	v_readfirstlane_b32 s36, v6
	v_readfirstlane_b32 s37, v7
	s_addc_u32 s28, s43, 0
	s_mov_b32 s29, 0
	v_mov_b64_e32 v[2:3], 0
	v_mov_b64_e32 v[4:5], 0
	v_mov_b64_e32 v[6:7], 0
	v_mov_b64_e32 v[8:9], 0
	v_mov_b64_e32 v[10:11], 0
	v_mov_b64_e32 v[12:13], 0
	v_mov_b64_e32 v[14:15], 0
	v_mov_b64_e32 v[16:17], 0
	v_mov_b64_e32 v[18:19], 0
	v_mov_b64_e32 v[20:21], 0
	v_mov_b64_e32 v[22:23], 0
	v_mov_b64_e32 v[24:25], 0
	v_mov_b64_e32 v[26:27], 0
	v_mov_b64_e32 v[28:29], 0
	v_mov_b64_e32 v[30:31], 0
	v_mov_b64_e32 v[32:33], 0
	v_mov_b64_e32 v[34:35], 0
	v_mov_b64_e32 v[36:37], 0
	v_mov_b64_e32 v[38:39], 0
	v_mov_b64_e32 v[40:41], 0
	v_mov_b64_e32 v[42:43], 0
	v_mov_b64_e32 v[44:45], 0
	v_mov_b64_e32 v[46:47], 0
	v_mov_b64_e32 v[48:49], 0
	v_mov_b64_e32 v[50:51], 0
	v_mov_b64_e32 v[52:53], 0
	v_mov_b64_e32 v[54:55], 0
	v_mov_b64_e32 v[56:57], 0
	v_mov_b64_e32 v[58:59], 0
	v_mov_b64_e32 v[60:61], 0
	v_mov_b64_e32 v[62:63], 0
	v_mov_b64_e32 v[64:65], 0
	v_mov_b64_e32 v[66:67], 0
	v_mov_b64_e32 v[68:69], 0
	v_mov_b64_e32 v[70:71], 0
	v_mov_b64_e32 v[72:73], 0
	v_mov_b64_e32 v[74:75], 0
	v_mov_b64_e32 v[76:77], 0
	v_mov_b64_e32 v[78:79], 0
	v_mov_b64_e32 v[82:83], 0
	v_mov_b64_e32 v[84:85], 0
	v_mov_b64_e32 v[86:87], 0
	v_mov_b64_e32 v[88:89], 0
	v_mov_b64_e32 v[90:91], 0
	v_mov_b64_e32 v[92:93], 0
	v_mov_b64_e32 v[94:95], 0
	v_mov_b64_e32 v[96:97], 0
	v_mov_b64_e32 v[98:99], 0
	v_mov_b64_e32 v[100:101], 0
	v_mov_b64_e32 v[102:103], 0
	v_mov_b64_e32 v[104:105], 0
	v_mov_b64_e32 v[106:107], 0
	v_mov_b64_e32 v[108:109], 0
	v_mov_b64_e32 v[110:111], 0
	v_mov_b64_e32 v[112:113], 0
	v_mov_b64_e32 v[114:115], 0
	v_mov_b64_e32 v[116:117], 0
	v_mov_b64_e32 v[118:119], 0
	v_mov_b64_e32 v[120:121], 0
	v_mov_b64_e32 v[122:123], 0
	v_mov_b64_e32 v[124:125], 0
	v_mov_b64_e32 v[126:127], 0
	v_mov_b64_e32 v[128:129], 0
	v_mov_b32_e32 v1, 0

; __device__ __forceinline__ void phase_fnet_combine(bf16_t* __restrict__ fg, const float* __restrict__ P, const float* __restrict__ Q, const float* __restrict__ P128, const float* __restrict__ PH, const int S) {
;     ...
;     if (hi) {
;       if (l0 == 128) ps = mid ? PH[seq * 2304 + 2048 + g] : P128[((size_t)seq * 4096 + kk) * 16 + g];
;       else { ps = Pr[g * 128 + 256 - l0]; qs = Qr[g * 128 + 256 - l0]; }
;     }
.LBB0_474:
	s_or_b64 exec, exec, s[6:7]
	s_nop 0
	v_mov_b32_e32 v46, v106
	v_mov_b32_e32 v47, 0

; __device__ __forceinline__ void phase_fnet_combine(bf16_t* __restrict__ fg, const float* __restrict__ P, const float* __restrict__ Q, const float* __restrict__ P128, const float* __restrict__ PH, const int S) {
;     ...
;     const size_t t = i >> 9; const int col = (int)(i & 511) * 8, g = col >> 8, l0 = col & 255;
;     const int seq = (int)(t / S), k = (int)(t % S);
;     const bool klo = (k <= S / 2); const int kk = klo ? k : S - k;
;     const bool mid = (kk == S / 2), hi = (l0 >= 128);
;     const float* Pr = mid ? PH + seq * 2304 : P + ((size_t)seq * 4096 + kk) * 2048;
;     const float* Qr = Q + ((size_t)seq * 4096 + (mid ? 0 : kk)) * 2048;
;     const int vb = g * 128 + (hi ? 248 - l0 : l0);
;     const f32x4 p0 = *(const f32x4*)(Pr + vb), p1 = *(const f32x4*)(Pr + vb + 4);
;     const f32x4 q0 = *(const f32x4*)(Qr + vb), q1 = *(const f32x4*)(Qr + vb + 4);
;     const float pw[8] = {p0[0], p0[1], p0[2], p0[3], p1[0], p1[1], p1[2], p1[3]}, qw[8] = {q0[0], q0[1], q0[2], q0[3], q1[0], q1[1], q1[2], q1[3]};
;     float ps = 0.f, qs = 0.f;
;     if (hi) {
;       if (l0 == 128) ps = mid ? PH[seq * 2304 + 2048 + g] : P128[((size_t)seq * 4096 + kk) * 16 + g];
;       else { ps = Pr[g * 128 + 256 - l0]; qs = Qr[g * 128 + 256 - l0]; }
;     }
.LBB0_477:
	v_alignbit_b32 v0, v37, v36, 9
	v_lshrrev_b32_e32 v80, s0, v0
	v_and_b32_e32 v0, s1, v0
	v_sub_u32_e32 v1, s17, v0
	v_cmp_lt_u32_e64 s[2:3], s40, v0
	s_nop 1
	v_cndmask_b32_e64 v0, v0, v1, s[2:3]
	v_cmp_eq_u32_e64 s[4:5], s40, v0
	v_cmp_ne_u32_e64 s[6:7], s40, v0
	s_and_saveexec_b64 s[8:9], s[6:7]
	s_xor_b64 s[8:9], exec, s[8:9]
	v_ashrrev_i32_e32 v1, 31, v0
	v_lshlrev_b64 v[2:3], 25, v[80:81]
	v_lshl_add_u64 v[2:3], s[94:95], 0, v[2:3]
	v_lshlrev_b64 v[4:5], 13, v[0:1]
	v_lshl_add_u64 v[2:3], v[2:3], 0, v[4:5]
	v_mov_b64_e32 v[4:5], v[0:1]
	s_andn2_saveexec_b64 s[8:9], s[8:9]
	v_mov_b64_e32 v[2:3], s[44:45]
	s_movk_i32 s13, 0x2400
	v_mad_u64_u32 v[2:3], s[18:19], v80, s13, v[2:3]
	v_mov_b64_e32 v[4:5], 0
	s_or_b64 exec, exec, s[8:9]
	v_lshlrev_b64 v[38:39], 12, v[80:81]
	v_lshl_add_u64 v[4:5], v[4:5], 0, v[38:39]
	v_lshlrev_b64 v[4:5], 13, v[4:5]
	s_movk_i32 s8, 0xf8
	v_and_b32_e32 v45, 0xf8, v44
	v_lshl_add_u64 v[40:41], s[96:97], 0, v[4:5]
	v_bitop3_b32 v4, v44, s8, v44 bitop3:0xc
	s_movk_i32 s8, 0x7f
	v_bfe_u32 v48, v44, 8, 4
	v_cmp_lt_u32_e32 vcc, s8, v45
	v_lshlrev_b32_e32 v1, 7, v48
	v_mov_b32_e32 v13, v81
	v_cndmask_b32_e32 v4, v45, v4, vcc
	v_add_lshl_u32 v12, v1, v4, 2
	v_lshl_add_u64 v[8:9], v[2:3], 0, v[12:13]
	v_lshl_add_u64 v[16:17], v[40:41], 0, v[12:13]
	s_movk_i32 s100, 0x80
	v_cmp_eq_u32_e64 s[100:101], s100, v45
	v_ashrrev_i32_e32 v109, 31, v0
	v_mov_b32_e32 v108, v0
	v_lshl_add_u64 v[108:109], v[38:39], 0, v[108:109]
	v_lshlrev_b64 v[108:109], 6, v[108:109]
	v_lshl_add_u64 v[108:109], s[42:43], 0, v[108:109]
	v_lshlrev_b32_e32 v110, 2, v48
	v_mov_b32_e32 v111, v81
	v_lshl_add_u64 v[108:109], v[108:109], 0, v[110:111]
	v_mul_u32_u24_e32 v110, 0x900, v80
	v_or_b32_e32 v110, v110, v48
	v_add_u32_e32 v110, 0x800, v110
	v_lshl_add_u64 v[112:113], v[110:111], 2, s[44:45]
	v_cndmask_b32_e64 v108, v108, v112, s[4:5]
	v_cndmask_b32_e64 v109, v109, v113, s[4:5]
	v_lshl_add_u64 v[112:113], v[8:9], 0, 32
	v_cndmask_b32_e64 v108, v112, v108, s[100:101]
	v_cndmask_b32_e64 v109, v113, v109, s[100:101]
	global_load_dword v106, v[108:109], off
	global_load_dword v107, v[16:17], off offset:32
	v_lshl_add_u64 v[104:105], v[36:37], 4, s[38:39]
	global_load_dwordx4 v[100:103], v[104:105], off
	global_load_dwordx4 v[4:7], v[8:9], off
	s_nop 0
	global_load_dwordx4 v[8:11], v[8:9], off offset:16
	s_nop 0
	global_load_dwordx4 v[12:15], v[16:17], off offset:16
	s_nop 0
	global_load_dwordx4 v[16:19], v[16:17], off
	v_mov_b32_e32 v47, 0
	v_mov_b32_e32 v49, 1.0
	v_mov_b32_e32 v46, 0
	s_waitcnt vmcnt(0) lgkmcnt(0)
	v_mov_b64_e32 v[30:31], v[6:7]
	v_mov_b64_e32 v[22:23], v[10:11]
	v_mov_b64_e32 v[26:27], v[14:15]
	v_mov_b64_e32 v[34:35], v[18:19]
	v_mov_b64_e32 v[20:21], v[8:9]
	v_mov_b64_e32 v[28:29], v[4:5]
	v_mov_b64_e32 v[24:25], v[12:13]
	v_mov_b64_e32 v[32:33], v[16:17]
	s_and_saveexec_b64 s[46:47], vcc
	s_cbranch_execz .LBB0_476
	s_movk_i32 s8, 0x80
	v_cmp_ne_u32_e64 s[8:9], s8, v45
	s_and_saveexec_b64 s[18:19], s[8:9]
	s_xor_b64 s[8:9], exec, s[18:19]
	s_cbranch_execz .LBB0_484
	v_sub_u32_e32 v0, v1, v45
	v_add_u32_e32 v80, 0x100, v0
	v_lshlrev_b64 v[0:1], 2, v[80:81]
	v_lshl_add_u64 v[2:3], v[2:3], 0, v[0:1]
	v_lshl_add_u64 v[0:1], v[40:41], 0, v[0:1]
	v_mov_b32_e32 v46, v106
	v_mov_b32_e32 v47, v107

; #define LAS __attribute__((address_space(3)))
; __device__ __forceinline__ void load_unit(LAS unsigned char* lds, int i, Unit& u) {
;   const LAS unsigned* w = (const LAS unsigned*)(lds + STAGE_BYTES) + i * 12;
;   unsigned v[10];
; #pragma unroll
;   for (int k = 0; k < 10; ++k) v[k] = __builtin_amdgcn_readfirstlane(w[k]);
;   u.a0 = (const char*)(((unsigned long long)v[1] << 32) | v[0]); u.b0 = (const char*)(((unsigned long long)v[3] << 32) | v[2]);
;   u.b1 = (const char*)(((unsigned long long)v[5] << 32) | v[4]); u.C = (char*)(((unsigned long long)v[7] << 32) | v[6]);
;   u.r0 = (int)v[8]; u.c0 = (int)v[9]; u.pad0 = 0; u.pad1 = 0;
; }
; template <class Epi>
; __device__ __forceinline__ void gemm_phase(LAS unsigned char* lds, const int K, const unsigned lda_b, const unsigned ldb_b, const Map& M, const Epi& E) {
;     ...
; #pragma unroll
;     for (int a = 0; a < 2; ++a)
; #pragma unroll
;       for (int b = 0; b < 2; ++b)
; #pragma unroll
;         for (int m = 0; m < 4; ++m)
; #pragma unroll
;           for (int n = 0; n < 2; ++n) acc[a][b][m][n] = (f32x4){0.f, 0.f, 0.f, 0.f};
.LBB0_553:
	s_mov_b32 s2, s66
	s_add_i32 s66, s66, 1
	s_cmp_lt_i32 s66, s1
	s_cselect_b32 s2, s66, s2
	s_mul_i32 s2, s2, 48
	s_add_i32 s2, s2, 0
	s_add_i32 s2, s2, 0x20000
	v_mov_b32_e32 v4, s2
	s_waitcnt lgkmcnt(0)
	ds_read_b128 v[0:3], v4
	ds_read_b64 v[130:131], v4 offset:32
	s_mov_b64 s[2:3], s[6:7]
	s_mov_b64 s[34:35], s[4:5]
	s_waitcnt lgkmcnt(0)
	v_readfirstlane_b32 s6, v2
	v_readfirstlane_b32 s7, v3
	s_add_u32 s28, s6, 0x40000
	s_addc_u32 s29, s7, 0
	s_add_u32 s30, s2, 0x40100
	s_addc_u32 s31, s3, 0
	v_readfirstlane_b32 s4, v0
	s_add_u32 s2, s34, 0x100080
	v_mov_b32_e32 v0, 0
	v_readfirstlane_b32 s5, v1
	s_addc_u32 s3, s35, 0
	s_mov_b32 s34, -2
	v_mov_b64_e32 v[2:3], 0
	v_mov_b64_e32 v[4:5], 0
	v_mov_b64_e32 v[6:7], 0
	v_mov_b64_e32 v[8:9], 0
	v_mov_b64_e32 v[10:11], 0
	v_mov_b64_e32 v[12:13], 0
	v_mov_b64_e32 v[14:15], 0
	v_mov_b64_e32 v[16:17], 0
	v_mov_b64_e32 v[18:19], 0
	v_mov_b64_e32 v[20:21], 0
	v_mov_b64_e32 v[22:23], 0
	v_mov_b64_e32 v[24:25], 0
	v_mov_b64_e32 v[26:27], 0
	v_mov_b64_e32 v[28:29], 0
	v_mov_b64_e32 v[30:31], 0
	v_mov_b64_e32 v[32:33], 0
	v_mov_b64_e32 v[34:35], 0
	v_mov_b64_e32 v[36:37], 0
	v_mov_b64_e32 v[38:39], 0
	v_mov_b64_e32 v[40:41], 0
	v_mov_b64_e32 v[42:43], 0
	v_mov_b64_e32 v[44:45], 0
	v_mov_b64_e32 v[46:47], 0
	v_mov_b64_e32 v[48:49], 0
	v_mov_b64_e32 v[50:51], 0
	v_mov_b64_e32 v[52:53], 0
	v_mov_b64_e32 v[54:55], 0
	v_mov_b64_e32 v[56:57], 0
	v_mov_b64_e32 v[58:59], 0
	v_mov_b64_e32 v[60:61], 0
	v_mov_b64_e32 v[62:63], 0
	v_mov_b64_e32 v[64:65], 0
	v_mov_b64_e32 v[66:67], 0
	v_mov_b64_e32 v[68:69], 0
	v_mov_b64_e32 v[70:71], 0
	v_mov_b64_e32 v[72:73], 0
	v_mov_b64_e32 v[74:75], 0
	v_mov_b64_e32 v[76:77], 0
	v_mov_b64_e32 v[78:79], 0
	v_mov_b64_e32 v[82:83], 0
	v_mov_b64_e32 v[84:85], 0
	v_mov_b64_e32 v[86:87], 0
	v_mov_b64_e32 v[88:89], 0
	v_mov_b64_e32 v[90:91], 0
	v_mov_b64_e32 v[92:93], 0
	v_mov_b64_e32 v[94:95], 0
	v_mov_b64_e32 v[96:97], 0
	v_mov_b64_e32 v[98:99], 0
	v_mov_b64_e32 v[100:101], 0
	v_mov_b64_e32 v[102:103], 0
	v_mov_b64_e32 v[104:105], 0
	v_mov_b64_e32 v[106:107], 0
	v_mov_b64_e32 v[108:109], 0
	v_mov_b64_e32 v[110:111], 0
	v_mov_b64_e32 v[112:113], 0
	v_mov_b64_e32 v[114:115], 0
	v_mov_b64_e32 v[116:117], 0
	v_mov_b64_e32 v[118:119], 0
	v_mov_b64_e32 v[120:121], 0
	v_mov_b64_e32 v[122:123], 0
	v_mov_b64_e32 v[124:125], 0
	v_mov_b64_e32 v[126:127], 0
	v_mov_b64_e32 v[128:129], 0
	v_mov_b32_e32 v1, 0

; #define LAS __attribute__((address_space(3)))
; __device__ __forceinline__ void load_unit(LAS unsigned char* lds, int i, Unit& u) {
;   const LAS unsigned* w = (const LAS unsigned*)(lds + STAGE_BYTES) + i * 12;
;   unsigned v[10];
; #pragma unroll
;   for (int k = 0; k < 10; ++k) v[k] = __builtin_amdgcn_readfirstlane(w[k]);
;   u.a0 = (const char*)(((unsigned long long)v[1] << 32) | v[0]); u.b0 = (const char*)(((unsigned long long)v[3] << 32) | v[2]);
;   u.b1 = (const char*)(((unsigned long long)v[5] << 32) | v[4]); u.C = (char*)(((unsigned long long)v[7] << 32) | v[6]);
;   u.r0 = (int)v[8]; u.c0 = (int)v[9]; u.pad0 = 0; u.pad1 = 0;
; }
; template <class Epi>
; __device__ __forceinline__ void gemm_phase(LAS unsigned char* lds, const int K, const unsigned lda_b, const unsigned ldb_b, const Map& M, const Epi& E) {
;     ...
; #pragma unroll
;     for (int a = 0; a < 2; ++a)
; #pragma unroll
;       for (int b = 0; b < 2; ++b)
; #pragma unroll
;         for (int m = 0; m < 4; ++m)
; #pragma unroll
;           for (int n = 0; n < 2; ++n) acc[a][b][m][n] = (f32x4){0.f, 0.f, 0.f, 0.f};
.LBB0_588:
	s_mov_b32 s2, s75
	s_add_i32 s75, s75, 1
	s_cmp_lt_i32 s75, s13
	s_cselect_b32 s2, s75, s2
	s_mul_i32 s2, s2, 48
	s_add_i32 s2, s2, 0
	s_add_i32 s2, s2, 0x20000
	v_mov_b32_e32 v4, s2
	ds_read_b128 v[0:3], v4
	ds_read2_b64 v[128:131], v4 offset0:3 offset1:4
	s_mov_b64 s[2:3], s[36:37]
	s_mov_b64 s[34:35], s[8:9]
	s_waitcnt lgkmcnt(0)
	v_readfirstlane_b32 s36, v2
	v_readfirstlane_b32 s37, v3
	s_add_u32 s28, s36, 0x20000
	s_addc_u32 s29, s37, 0
	s_add_u32 s30, s2, 0x20100
	s_addc_u32 s31, s3, 0
	v_readfirstlane_b32 s8, v0
	s_add_u32 s2, s34, 0x80080
	v_mov_b32_e32 v0, 0
	v_readfirstlane_b32 s9, v1
	v_readfirstlane_b32 s94, v128
	v_readfirstlane_b32 s95, v129
	s_addc_u32 s3, s35, 0
	s_mov_b32 s34, -2
	v_mov_b64_e32 v[2:3], 0
	v_mov_b64_e32 v[4:5], 0
	v_mov_b64_e32 v[6:7], 0
	v_mov_b64_e32 v[8:9], 0
	v_mov_b64_e32 v[10:11], 0
	v_mov_b64_e32 v[12:13], 0
	v_mov_b64_e32 v[14:15], 0
	v_mov_b64_e32 v[16:17], 0
	v_mov_b64_e32 v[18:19], 0
	v_mov_b64_e32 v[20:21], 0
	v_mov_b64_e32 v[22:23], 0
	v_mov_b64_e32 v[24:25], 0
	v_mov_b64_e32 v[26:27], 0
	v_mov_b64_e32 v[28:29], 0
	v_mov_b64_e32 v[30:31], 0
	v_mov_b64_e32 v[32:33], 0
	v_mov_b64_e32 v[34:35], 0
	v_mov_b64_e32 v[36:37], 0
	v_mov_b64_e32 v[38:39], 0
	v_mov_b64_e32 v[40:41], 0
	v_mov_b64_e32 v[42:43], 0
	v_mov_b64_e32 v[44:45], 0
	v_mov_b64_e32 v[46:47], 0
	v_mov_b64_e32 v[48:49], 0
	v_mov_b64_e32 v[50:51], 0
	v_mov_b64_e32 v[52:53], 0
	v_mov_b64_e32 v[54:55], 0
	v_mov_b64_e32 v[56:57], 0
	v_mov_b64_e32 v[58:59], 0
	v_mov_b64_e32 v[60:61], 0
	v_mov_b64_e32 v[62:63], 0
	v_mov_b64_e32 v[64:65], 0
	v_mov_b64_e32 v[66:67], 0
	v_mov_b64_e32 v[68:69], 0
	v_mov_b64_e32 v[70:71], 0
	v_mov_b64_e32 v[72:73], 0
	v_mov_b64_e32 v[74:75], 0
	v_mov_b64_e32 v[76:77], 0
	v_mov_b64_e32 v[78:79], 0
	v_mov_b64_e32 v[82:83], 0
	v_mov_b64_e32 v[84:85], 0
	v_mov_b64_e32 v[86:87], 0
	v_mov_b64_e32 v[88:89], 0
	v_mov_b64_e32 v[90:91], 0
	v_mov_b64_e32 v[92:93], 0
	v_mov_b64_e32 v[94:95], 0
	v_mov_b64_e32 v[96:97], 0
	v_mov_b64_e32 v[98:99], 0
	v_mov_b64_e32 v[100:101], 0
	v_mov_b64_e32 v[102:103], 0
	v_mov_b64_e32 v[104:105], 0
	v_mov_b64_e32 v[106:107], 0
	v_mov_b64_e32 v[108:109], 0
	v_mov_b64_e32 v[110:111], 0
	v_mov_b64_e32 v[112:113], 0
	v_mov_b64_e32 v[114:115], 0
	v_mov_b64_e32 v[116:117], 0
	v_mov_b64_e32 v[118:119], 0
	v_mov_b64_e32 v[120:121], 0
	v_mov_b64_e32 v[122:123], 0
	v_mov_b64_e32 v[124:125], 0
	v_mov_b64_e32 v[126:127], 0
	v_mov_b64_e32 v[128:129], 0
	v_mov_b32_e32 v1, 0

; #define LAS __attribute__((address_space(3)))
; __device__ __forceinline__ void load_unit(LAS unsigned char* lds, int i, Unit& u) {
;   const LAS unsigned* w = (const LAS unsigned*)(lds + STAGE_BYTES) + i * 12;
;   unsigned v[10];
; #pragma unroll
;   for (int k = 0; k < 10; ++k) v[k] = __builtin_amdgcn_readfirstlane(w[k]);
;   u.a0 = (const char*)(((unsigned long long)v[1] << 32) | v[0]); u.b0 = (const char*)(((unsigned long long)v[3] << 32) | v[2]);
;   u.b1 = (const char*)(((unsigned long long)v[5] << 32) | v[4]); u.C = (char*)(((unsigned long long)v[7] << 32) | v[6]);
;   u.r0 = (int)v[8]; u.c0 = (int)v[9]; u.pad0 = 0; u.pad1 = 0;
; }
; template <class Epi>
; __device__ __forceinline__ void gemm_phase(LAS unsigned char* lds, const int K, const unsigned lda_b, const unsigned ldb_b, const Map& M, const Epi& E) {
;     ...
; #pragma unroll
;     for (int a = 0; a < 2; ++a)
; #pragma unroll
;       for (int b = 0; b < 2; ++b)
; #pragma unroll
;         for (int m = 0; m < 4; ++m)
; #pragma unroll
;           for (int n = 0; n < 2; ++n) acc[a][b][m][n] = (f32x4){0.f, 0.f, 0.f, 0.f};
.LBB0_625:
	s_mov_b32 s8, s75
	s_add_i32 s75, s75, 1
	s_cmp_lt_i32 s75, s0
	s_cselect_b32 s8, s75, s8
	s_mul_i32 s8, s8, 48
	s_add_i32 s8, s8, 0
	s_add_i32 s8, s8, 0x20000
	v_mov_b32_e32 v0, s8
	ds_read_b128 v[4:7], v0
	ds_read2_b64 v[0:3], v0 offset0:3 offset1:4
	s_mov_b32 s34, -2
	s_waitcnt lgkmcnt(0)
	v_readfirstlane_b32 s40, v6
	v_readfirstlane_b32 s41, v7
	s_add_u32 s28, s40, 0x20000
	s_addc_u32 s29, s41, 0
	s_add_u32 s30, s68, 0x20100
	s_addc_u32 s31, s69, 0
	v_readfirstlane_b32 s36, v4
	s_add_u32 s38, s44, 0x80080
	v_mov_b32_e32 v4, 0
	v_readfirstlane_b32 s37, v5
	v_readfirstlane_b32 s8, v0
	v_readfirstlane_b32 s9, v1
	s_addc_u32 s39, s45, 0
	v_mov_b64_e32 v[6:7], 0
	v_mov_b64_e32 v[8:9], 0
	v_mov_b64_e32 v[10:11], 0
	v_mov_b64_e32 v[12:13], 0
	v_mov_b64_e32 v[14:15], 0
	v_mov_b64_e32 v[16:17], 0
	v_mov_b64_e32 v[18:19], 0
	v_mov_b64_e32 v[20:21], 0
	v_mov_b64_e32 v[22:23], 0
	v_mov_b64_e32 v[24:25], 0
	v_mov_b64_e32 v[26:27], 0
	v_mov_b64_e32 v[28:29], 0
	v_mov_b64_e32 v[30:31], 0
	v_mov_b64_e32 v[32:33], 0
	v_mov_b64_e32 v[34:35], 0
	v_mov_b64_e32 v[36:37], 0
	v_mov_b64_e32 v[38:39], 0
	v_mov_b64_e32 v[40:41], 0
	v_mov_b64_e32 v[42:43], 0
	v_mov_b64_e32 v[44:45], 0
	v_mov_b64_e32 v[46:47], 0
	v_mov_b64_e32 v[48:49], 0
	v_mov_b64_e32 v[50:51], 0
	v_mov_b64_e32 v[52:53], 0
	v_mov_b64_e32 v[54:55], 0
	v_mov_b64_e32 v[56:57], 0
	v_mov_b64_e32 v[58:59], 0
	v_mov_b64_e32 v[60:61], 0
	v_mov_b64_e32 v[62:63], 0
	v_mov_b64_e32 v[64:65], 0
	v_mov_b64_e32 v[66:67], 0
	v_mov_b64_e32 v[68:69], 0
	v_mov_b64_e32 v[70:71], 0
	v_mov_b64_e32 v[72:73], 0
	v_mov_b64_e32 v[74:75], 0
	v_mov_b64_e32 v[76:77], 0
	v_mov_b64_e32 v[78:79], 0
	v_mov_b64_e32 v[82:83], 0
	v_mov_b64_e32 v[84:85], 0
	v_mov_b64_e32 v[86:87], 0
	v_mov_b64_e32 v[88:89], 0
	v_mov_b64_e32 v[90:91], 0
	v_mov_b64_e32 v[92:93], 0
	v_mov_b64_e32 v[94:95], 0
	v_mov_b64_e32 v[96:97], 0
	v_mov_b64_e32 v[98:99], 0
	v_mov_b64_e32 v[100:101], 0
	v_mov_b64_e32 v[102:103], 0
	v_mov_b64_e32 v[104:105], 0
	v_mov_b64_e32 v[106:107], 0
	v_mov_b64_e32 v[108:109], 0
	v_mov_b64_e32 v[110:111], 0
	v_mov_b64_e32 v[112:113], 0
	v_mov_b64_e32 v[114:115], 0
	v_mov_b64_e32 v[116:117], 0
	v_mov_b64_e32 v[118:119], 0
	v_mov_b64_e32 v[120:121], 0
	v_mov_b64_e32 v[122:123], 0
	v_mov_b64_e32 v[124:125], 0
	v_mov_b64_e32 v[126:127], 0
	v_mov_b64_e32 v[128:129], 0
	v_mov_b64_e32 v[130:131], 0
	v_mov_b64_e32 v[132:133], 0
	v_mov_b32_e32 v5, 0

; #define LAS __attribute__((address_space(3)))
; __device__ __forceinline__ void load_unit(LAS unsigned char* lds, int i, Unit& u) {
;   const LAS unsigned* w = (const LAS unsigned*)(lds + STAGE_BYTES) + i * 12;
;   unsigned v[10];
; #pragma unroll
;   for (int k = 0; k < 10; ++k) v[k] = __builtin_amdgcn_readfirstlane(w[k]);
;   u.a0 = (const char*)(((unsigned long long)v[1] << 32) | v[0]); u.b0 = (const char*)(((unsigned long long)v[3] << 32) | v[2]);
;   u.b1 = (const char*)(((unsigned long long)v[5] << 32) | v[4]); u.C = (char*)(((unsigned long long)v[7] << 32) | v[6]);
;   u.r0 = (int)v[8]; u.c0 = (int)v[9]; u.pad0 = 0; u.pad1 = 0;
; }
; template <class Epi>
; __device__ __forceinline__ void gemm_phase(LAS unsigned char* lds, const int K, const unsigned lda_b, const unsigned ldb_b, const Map& M, const Epi& E) {
;     ...
; #pragma unroll
;     for (int a = 0; a < 2; ++a)
; #pragma unroll
;       for (int b = 0; b < 2; ++b)
; #pragma unroll
;         for (int m = 0; m < 4; ++m)
; #pragma unroll
;           for (int n = 0; n < 2; ++n) acc[a][b][m][n] = (f32x4){0.f, 0.f, 0.f, 0.f};
.LBB0_650:
	s_mov_b32 s0, s96
	s_add_i32 s96, s96, 1
	s_cmp_lt_i32 s96, s13
	s_cselect_b32 s0, s96, s0
	s_mul_i32 s0, s0, 48
	s_add_i32 s0, s0, 0
	s_add_i32 s0, s0, 0x20000
	v_mov_b32_e32 v4, s0
	ds_read_b128 v[0:3], v4
	ds_read2_b64 v[128:131], v4 offset0:3 offset1:4
	s_mov_b32 s31, -2
	s_waitcnt lgkmcnt(0)
	v_readfirstlane_b32 s36, v2
	v_readfirstlane_b32 s37, v3
	s_add_u32 s0, s36, s46
	s_addc_u32 s28, s37, 0
	s_add_u32 s29, s38, 0x100
	s_addc_u32 s30, s39, 0
	v_readfirstlane_b32 s8, v0
	s_add_u32 s2, s2, 0x80080
	v_mov_b32_e32 v0, 0
	v_readfirstlane_b32 s9, v1
	v_readfirstlane_b32 s40, v128
	v_readfirstlane_b32 s41, v129
	s_addc_u32 s3, s3, 0
	v_mov_b64_e32 v[2:3], 0
	v_mov_b64_e32 v[4:5], 0
	v_mov_b64_e32 v[6:7], 0
	v_mov_b64_e32 v[8:9], 0
	v_mov_b64_e32 v[10:11], 0
	v_mov_b64_e32 v[12:13], 0
	v_mov_b64_e32 v[14:15], 0
	v_mov_b64_e32 v[16:17], 0
	v_mov_b64_e32 v[18:19], 0
	v_mov_b64_e32 v[20:21], 0
	v_mov_b64_e32 v[22:23], 0
	v_mov_b64_e32 v[24:25], 0
	v_mov_b64_e32 v[26:27], 0
	v_mov_b64_e32 v[28:29], 0
	v_mov_b64_e32 v[30:31], 0
	v_mov_b64_e32 v[32:33], 0
	v_mov_b64_e32 v[34:35], 0
	v_mov_b64_e32 v[36:37], 0
	v_mov_b64_e32 v[38:39], 0
	v_mov_b64_e32 v[40:41], 0
	v_mov_b64_e32 v[42:43], 0
	v_mov_b64_e32 v[44:45], 0
	v_mov_b64_e32 v[46:47], 0
	v_mov_b64_e32 v[48:49], 0
	v_mov_b64_e32 v[50:51], 0
	v_mov_b64_e32 v[52:53], 0
	v_mov_b64_e32 v[54:55], 0
	v_mov_b64_e32 v[56:57], 0
	v_mov_b64_e32 v[58:59], 0
	v_mov_b64_e32 v[60:61], 0
	v_mov_b64_e32 v[62:63], 0
	v_mov_b64_e32 v[64:65], 0
	v_mov_b64_e32 v[66:67], 0
	v_mov_b64_e32 v[68:69], 0
	v_mov_b64_e32 v[70:71], 0
	v_mov_b64_e32 v[72:73], 0
	v_mov_b64_e32 v[74:75], 0
	v_mov_b64_e32 v[76:77], 0
	v_mov_b64_e32 v[78:79], 0
	v_mov_b64_e32 v[82:83], 0
	v_mov_b64_e32 v[84:85], 0
	v_mov_b64_e32 v[86:87], 0
	v_mov_b64_e32 v[88:89], 0
	v_mov_b64_e32 v[90:91], 0
	v_mov_b64_e32 v[92:93], 0
	v_mov_b64_e32 v[94:95], 0
	v_mov_b64_e32 v[96:97], 0
	v_mov_b64_e32 v[98:99], 0
	v_mov_b64_e32 v[100:101], 0
	v_mov_b64_e32 v[102:103], 0
	v_mov_b64_e32 v[104:105], 0
	v_mov_b64_e32 v[106:107], 0
	v_mov_b64_e32 v[108:109], 0
	v_mov_b64_e32 v[110:111], 0
	v_mov_b64_e32 v[112:113], 0
	v_mov_b64_e32 v[114:115], 0
	v_mov_b64_e32 v[116:117], 0
	v_mov_b64_e32 v[118:119], 0
	v_mov_b64_e32 v[120:121], 0
	v_mov_b64_e32 v[122:123], 0
	v_mov_b64_e32 v[124:125], 0
	v_mov_b64_e32 v[126:127], 0
	v_mov_b64_e32 v[128:129], 0
	v_mov_b32_e32 v1, 0

; #define LAS __attribute__((address_space(3)))
; __device__ __forceinline__ void load_unit(LAS unsigned char* lds, int i, Unit& u) {
;   const LAS unsigned* w = (const LAS unsigned*)(lds + STAGE_BYTES) + i * 12;
;   unsigned v[10];
; #pragma unroll
;   for (int k = 0; k < 10; ++k) v[k] = __builtin_amdgcn_readfirstlane(w[k]);
;   u.a0 = (const char*)(((unsigned long long)v[1] << 32) | v[0]); u.b0 = (const char*)(((unsigned long long)v[3] << 32) | v[2]);
;   u.b1 = (const char*)(((unsigned long long)v[5] << 32) | v[4]); u.C = (char*)(((unsigned long long)v[7] << 32) | v[6]);
;   u.r0 = (int)v[8]; u.c0 = (int)v[9]; u.pad0 = 0; u.pad1 = 0;
; }
; template <class Epi>
; __device__ __forceinline__ void gemm_phase(LAS unsigned char* lds, const int K, const unsigned lda_b, const unsigned ldb_b, const Map& M, const Epi& E) {
;     ...
; #pragma unroll
;     for (int a = 0; a < 2; ++a)
; #pragma unroll
;       for (int b = 0; b < 2; ++b)
; #pragma unroll
;         for (int m = 0; m < 4; ++m)
; #pragma unroll
;           for (int n = 0; n < 2; ++n) acc[a][b][m][n] = (f32x4){0.f, 0.f, 0.f, 0.f};
.LBB0_843:
	s_mov_b32 s2, s61
	s_add_i32 s61, s61, 1
	s_cmp_lt_i32 s61, s1
	s_cselect_b32 s2, s61, s2
	s_mul_i32 s2, s2, 48
	s_add_i32 s2, s2, 0
	s_add_i32 s2, s2, 0x20000
	v_mov_b32_e32 v4, s2
	s_waitcnt lgkmcnt(0)
	ds_read_b128 v[0:3], v4
	ds_read_b64 v[130:131], v4 offset:32
	s_mov_b64 s[2:3], s[6:7]
	s_mov_b64 s[34:35], s[4:5]
	s_waitcnt lgkmcnt(0)
	v_readfirstlane_b32 s6, v2
	v_readfirstlane_b32 s7, v3
	s_add_u32 s28, s6, 0x20000
	s_addc_u32 s29, s7, 0
	s_add_u32 s30, s2, 0x20100
	s_addc_u32 s31, s3, 0
	v_readfirstlane_b32 s4, v0
	s_add_u32 s2, s34, 0x80080
	v_mov_b32_e32 v0, 0
	v_readfirstlane_b32 s5, v1
	s_addc_u32 s3, s35, 0
	s_mov_b32 s34, -2
	v_mov_b64_e32 v[2:3], 0
	v_mov_b64_e32 v[4:5], 0
	v_mov_b64_e32 v[6:7], 0
	v_mov_b64_e32 v[8:9], 0
	v_mov_b64_e32 v[10:11], 0
	v_mov_b64_e32 v[12:13], 0
	v_mov_b64_e32 v[14:15], 0
	v_mov_b64_e32 v[16:17], 0
	v_mov_b64_e32 v[18:19], 0
	v_mov_b64_e32 v[20:21], 0
	v_mov_b64_e32 v[22:23], 0
	v_mov_b64_e32 v[24:25], 0
	v_mov_b64_e32 v[26:27], 0
	v_mov_b64_e32 v[28:29], 0
	v_mov_b64_e32 v[30:31], 0
	v_mov_b64_e32 v[32:33], 0
	v_mov_b64_e32 v[34:35], 0
	v_mov_b64_e32 v[36:37], 0
	v_mov_b64_e32 v[38:39], 0
	v_mov_b64_e32 v[40:41], 0
	v_mov_b64_e32 v[42:43], 0
	v_mov_b64_e32 v[44:45], 0
	v_mov_b64_e32 v[46:47], 0
	v_mov_b64_e32 v[48:49], 0
	v_mov_b64_e32 v[50:51], 0
	v_mov_b64_e32 v[52:53], 0
	v_mov_b64_e32 v[54:55], 0
	v_mov_b64_e32 v[56:57], 0
	v_mov_b64_e32 v[58:59], 0
	v_mov_b64_e32 v[60:61], 0
	v_mov_b64_e32 v[62:63], 0
	v_mov_b64_e32 v[64:65], 0
	v_mov_b64_e32 v[66:67], 0
	v_mov_b64_e32 v[68:69], 0
	v_mov_b64_e32 v[70:71], 0
	v_mov_b64_e32 v[72:73], 0
	v_mov_b64_e32 v[74:75], 0
	v_mov_b64_e32 v[76:77], 0
	v_mov_b64_e32 v[78:79], 0
	v_mov_b64_e32 v[82:83], 0
	v_mov_b64_e32 v[84:85], 0
	v_mov_b64_e32 v[86:87], 0
	v_mov_b64_e32 v[88:89], 0
	v_mov_b64_e32 v[90:91], 0
	v_mov_b64_e32 v[92:93], 0
	v_mov_b64_e32 v[94:95], 0
	v_mov_b64_e32 v[96:97], 0
	v_mov_b64_e32 v[98:99], 0
	v_mov_b64_e32 v[100:101], 0
	v_mov_b64_e32 v[102:103], 0
	v_mov_b64_e32 v[104:105], 0
	v_mov_b64_e32 v[106:107], 0
	v_mov_b64_e32 v[108:109], 0
	v_mov_b64_e32 v[110:111], 0
	v_mov_b64_e32 v[112:113], 0
	v_mov_b64_e32 v[114:115], 0
	v_mov_b64_e32 v[116:117], 0
	v_mov_b64_e32 v[118:119], 0
	v_mov_b64_e32 v[120:121], 0
	v_mov_b64_e32 v[122:123], 0
	v_mov_b64_e32 v[124:125], 0
	v_mov_b64_e32 v[126:127], 0
	v_mov_b64_e32 v[128:129], 0
	v_mov_b32_e32 v1, 0

; #define LAS __attribute__((address_space(3)))
; __device__ __forceinline__ void load_unit(LAS unsigned char* lds, int i, Unit& u) {
;   const LAS unsigned* w = (const LAS unsigned*)(lds + STAGE_BYTES) + i * 12;
;   unsigned v[10];
; #pragma unroll
;   for (int k = 0; k < 10; ++k) v[k] = __builtin_amdgcn_readfirstlane(w[k]);
;   u.a0 = (const char*)(((unsigned long long)v[1] << 32) | v[0]); u.b0 = (const char*)(((unsigned long long)v[3] << 32) | v[2]);
;   u.b1 = (const char*)(((unsigned long long)v[5] << 32) | v[4]); u.C = (char*)(((unsigned long long)v[7] << 32) | v[6]);
;   u.r0 = (int)v[8]; u.c0 = (int)v[9]; u.pad0 = 0; u.pad1 = 0;
; }
; template <class Epi>
; __device__ __forceinline__ void gemm_phase(LAS unsigned char* lds, const int K, const unsigned lda_b, const unsigned ldb_b, const Map& M, const Epi& E) {
;     ...
; #pragma unroll
;     for (int a = 0; a < 2; ++a)
; #pragma unroll
;       for (int b = 0; b < 2; ++b)
; #pragma unroll
;         for (int m = 0; m < 4; ++m)
; #pragma unroll
;           for (int n = 0; n < 2; ++n) acc[a][b][m][n] = (f32x4){0.f, 0.f, 0.f, 0.f};
.LBB0_957:
	s_mov_b32 s1, s82
	s_add_i32 s82, s82, 1
	s_cmp_lt_i32 s82, s13
	s_cselect_b32 s1, s82, s1
	s_mul_i32 s1, s1, 48
	s_add_i32 s1, s1, 0
	s_add_i32 s1, s1, 0x20000
	v_mov_b32_e32 v4, s1
	s_waitcnt lgkmcnt(0)
	ds_read_b128 v[0:3], v4
	ds_read2_b64 v[120:123], v4 offset0:3 offset1:4
	s_mov_b64 s[4:5], s[8:9]
	s_mov_b64 s[30:31], s[6:7]
	s_mov_b32 s29, -2
	s_waitcnt lgkmcnt(0)
	v_readfirstlane_b32 s8, v2
	v_readfirstlane_b32 s9, v3
	s_add_u32 s1, s8, 0x20000
	s_addc_u32 s18, s9, 0
	s_add_u32 s19, s4, 0x20100
	s_addc_u32 s28, s5, 0
	v_readfirstlane_b32 s6, v0
	s_add_u32 s4, s30, 0x80080
	v_mov_b32_e32 v0, 0
	v_readfirstlane_b32 s7, v1
	v_readfirstlane_b32 s40, v120
	v_readfirstlane_b32 s41, v121
	s_addc_u32 s5, s31, 0
	v_mov_b64_e32 v[2:3], 0
	v_mov_b64_e32 v[4:5], 0
	v_mov_b64_e32 v[6:7], 0
	v_mov_b64_e32 v[8:9], 0
	v_mov_b64_e32 v[10:11], 0
	v_mov_b64_e32 v[12:13], 0
	v_mov_b64_e32 v[14:15], 0
	v_mov_b64_e32 v[16:17], 0
	v_mov_b64_e32 v[18:19], 0
	v_mov_b64_e32 v[20:21], 0
	v_mov_b64_e32 v[22:23], 0
	v_mov_b64_e32 v[24:25], 0
	v_mov_b64_e32 v[26:27], 0
	v_mov_b64_e32 v[28:29], 0
	v_mov_b64_e32 v[30:31], 0
	v_mov_b64_e32 v[32:33], 0
	v_mov_b64_e32 v[34:35], 0
	v_mov_b64_e32 v[36:37], 0
	v_mov_b64_e32 v[38:39], 0
	v_mov_b64_e32 v[40:41], 0
	v_mov_b64_e32 v[42:43], 0
	v_mov_b64_e32 v[44:45], 0
	v_mov_b64_e32 v[46:47], 0
	v_mov_b64_e32 v[48:49], 0
	v_mov_b64_e32 v[50:51], 0
	v_mov_b64_e32 v[52:53], 0
	v_mov_b64_e32 v[54:55], 0
	v_mov_b64_e32 v[56:57], 0
	v_mov_b64_e32 v[58:59], 0
	v_mov_b64_e32 v[60:61], 0
	v_mov_b64_e32 v[62:63], 0
	v_mov_b64_e32 v[64:65], 0
	v_mov_b64_e32 v[66:67], 0
	v_mov_b64_e32 v[68:69], 0
	v_mov_b64_e32 v[70:71], 0
	v_mov_b64_e32 v[72:73], 0
	v_mov_b64_e32 v[74:75], 0
	v_mov_b64_e32 v[76:77], 0
	v_mov_b64_e32 v[78:79], 0
	v_mov_b64_e32 v[82:83], 0
	v_mov_b64_e32 v[84:85], 0
	v_mov_b64_e32 v[86:87], 0
	v_mov_b64_e32 v[88:89], 0
	v_mov_b64_e32 v[90:91], 0
	v_mov_b64_e32 v[92:93], 0
	v_mov_b64_e32 v[94:95], 0
	v_mov_b64_e32 v[96:97], 0
	v_mov_b64_e32 v[98:99], 0
	v_mov_b64_e32 v[100:101], 0
	v_mov_b64_e32 v[102:103], 0
	v_mov_b64_e32 v[104:105], 0
	v_mov_b64_e32 v[106:107], 0
	v_mov_b64_e32 v[108:109], 0
	v_mov_b64_e32 v[110:111], 0
	v_mov_b64_e32 v[112:113], 0
	v_mov_b64_e32 v[114:115], 0
	v_mov_b64_e32 v[116:117], 0
	v_mov_b64_e32 v[118:119], 0
	v_mov_b64_e32 v[120:121], 0
	v_mov_b64_e32 v[124:125], 0
	v_mov_b64_e32 v[126:127], 0
	v_mov_b64_e32 v[128:129], 0
	v_mov_b64_e32 v[130:131], 0
	v_mov_b32_e32 v1, 0

; __global__ void __launch_bounds__(512, 2) mega(Params p) {
	.amdhsa_kernel _Z4mega6Params
		.amdhsa_group_segment_fixed_size 0
		.amdhsa_private_segment_fixed_size 0
		.amdhsa_kernarg_size 384
		.amdhsa_user_sgpr_count 2
		.amdhsa_user_sgpr_dispatch_ptr 0
		.amdhsa_user_sgpr_queue_ptr 0
		.amdhsa_user_sgpr_kernarg_segment_ptr 1
		.amdhsa_user_sgpr_dispatch_id 0
		.amdhsa_user_sgpr_kernarg_preload_length 0
		.amdhsa_user_sgpr_kernarg_preload_offset 0
		.amdhsa_user_sgpr_private_segment_size 0
		.amdhsa_uses_dynamic_stack 0
		.amdhsa_enable_private_segment 0
		.amdhsa_system_sgpr_workgroup_id_x 1
		.amdhsa_system_sgpr_workgroup_id_y 0
		.amdhsa_system_sgpr_workgroup_id_z 0
		.amdhsa_system_sgpr_workgroup_info 0
		.amdhsa_system_vgpr_workitem_id 2
		.amdhsa_next_free_vgpr 256
		.amdhsa_next_free_sgpr 102
		.amdhsa_accum_offset 256
		.amdhsa_reserve_vcc 1
		.amdhsa_float_round_mode_32 0
		.amdhsa_float_round_mode_16_64 0
		.amdhsa_float_denorm_mode_32 3
		.amdhsa_float_denorm_mode_16_64 3
		.amdhsa_dx10_clamp 1
		.amdhsa_ieee_mode 1
		.amdhsa_fp16_overflow 0
		.amdhsa_tg_split 0
		.amdhsa_exception_fp_ieee_invalid_op 0
		.amdhsa_exception_fp_denorm_src 0
		.amdhsa_exception_fp_ieee_div_zero 0
		.amdhsa_exception_fp_ieee_overflow 0
		.amdhsa_exception_fp_ieee_underflow 0
		.amdhsa_exception_fp_ieee_inexact 0
		.amdhsa_exception_int_div_zero 0
	.end_amdhsa_kernel

; __global__ void __launch_bounds__(512, 2) mega(Params p) {
amdhsa.kernels:
  - .agpr_count:     0
    .args:
      - .offset:         0
        .size:           128
        .value_kind:     by_value
      - .offset:         128
        .size:           4
        .value_kind:     hidden_block_count_x
      - .offset:         132
        .size:           4
        .value_kind:     hidden_block_count_y
      - .offset:         136
        .size:           4
        .value_kind:     hidden_block_count_z
      - .offset:         140
        .size:           2
        .value_kind:     hidden_group_size_x
      - .offset:         142
        .size:           2
        .value_kind:     hidden_group_size_y
      - .offset:         144
        .size:           2
        .value_kind:     hidden_group_size_z
      - .offset:         146
        .size:           2
        .value_kind:     hidden_remainder_x
      - .offset:         148
        .size:           2
        .value_kind:     hidden_remainder_y
      - .offset:         150
        .size:           2
        .value_kind:     hidden_remainder_z
      - .offset:         168
        .size:           8
        .value_kind:     hidden_global_offset_x
      - .offset:         176
        .size:           8
        .value_kind:     hidden_global_offset_y
      - .offset:         184
        .size:           8
        .value_kind:     hidden_global_offset_z
      - .offset:         192
        .size:           2
        .value_kind:     hidden_grid_dims
      - .offset:         216
        .size:           8
        .value_kind:     hidden_multigrid_sync_arg
      - .offset:         248
        .size:           4
        .value_kind:     hidden_dynamic_lds_size
    .group_segment_fixed_size: 0
    .kernarg_segment_align: 8
    .kernarg_segment_size: 384
    .language:       OpenCL C
    .language_version:
      - 2
      - 0
    .max_flat_workgroup_size: 512
    .name:           _Z4mega6Params
    .private_segment_fixed_size: 0
    .sgpr_count:     108
    .sgpr_spill_count: 38
    .symbol:         _Z4mega6Params.kd
    .uniform_work_group_size: 1
    .uses_dynamic_stack: false
    .vgpr_count:     256
    .vgpr_spill_count: 0
    .wavefront_size: 64
